# stack3: + attention loop trims (redundant self-max canonicalisations and alpha==1 test removed, rescale blocks out of line, static staging conditionals stripped in the unrolled fast loop)
# baseline (speedup 1.0000x reference)
; #define SBAR() __builtin_amdgcn_sched_barrier(0)
; #define ABAR() asm volatile("s_waitcnt lgkmcnt(0)\n\ts_barrier" ::: "memory")
; #define SLOAD(i, k0) do { const bf16_t* vt_ = Vh + (size_t)(k0) * 512; const bf16_t* kt_ = KNh + (size_t)(k0) * 512; const bf16_t* rt_ = KRb + (size_t)(k0) * 32; \
;     sr_[i].vs = *reinterpret_cast<const bf16x8*>(vt_ + lo_kv); sr_[i].ks = *reinterpret_cast<const bf16x8*>(kt_ + lo_kv); sr_[i].kr = *reinterpret_cast<const s16x4*>(rt_ + lo_kr); } while (0)
; #define SWRITE(slot, i) do { *(bf16x8*)(V_lds + (slot) * SHM_V + vst) = sr_[i].vs; *(bf16x8*)(K_lds + (slot) * SHM_K + kst) = sr_[i].ks; *(s16x4*)(K_lds + (slot) * SHM_K + krst) = sr_[i].kr; } while (0)
; #define RESC(a) do { if (__any((a) < 1.f)) { if (hi == 0) al_l[r32] = (a); asm volatile("s_waitcnt lgkmcnt(0)" ::: "memory"); \
;     _Pragma("unroll") for (int d = 0; d < 2; ++d) _Pragma("unroll") for (int r = 0; r < 16; ++r) o[d][r] *= al_l[crow(r, hi)]; } } while (0)
; template <bool FIRST> __device__ __forceinline__ void partialSM(f32x16& p0, f32x16& p1, float& mref, f32x16& negm, float& alpha) {
;   constexpr float THRL = THR * 1.4426950408889634f;
;   float pmax = p0[0];
; #pragma unroll
;   for (int r = 1; r < 16; ++r) pmax = fmaxf(pmax, p0[r]);
; #pragma unroll
;   for (int r = 0; r < 16; ++r) pmax = fmaxf(pmax, p1[r]);
;   { auto rr = __builtin_amdgcn_permlane32_swap(__float_as_uint(pmax), __float_as_uint(pmax), false, false);
;     pmax = fmaxf(__uint_as_float(rr[0]), __uint_as_float(rr[1])); }
;   if (!FIRST && __builtin_expect(__all(pmax <= THRL), 1)) { alpha = 1.f; }
; __device__ __forceinline__ void attn_unit(const bf16_t* __restrict__ Qb, const bf16_t* __restrict__ KNh, const bf16_t* __restrict__ KRb, const bf16_t* __restrict__ Vh, bf16_t* __restrict__ Ob, char* lds) {
;     ...
;   for (int j = 1; j + 1 < NT; j += 2) {
;     SBAR(); qkt(pB0, pB1, K_lds + (j & 3) * SHM_K, qr, negm, r32, hi);
;     finishSM(pA0, pA1, alA, l_reg, pa0, pa1, pa2, pa3); SBAR();
;     if (j + 2 < NT) { SWRITE((j + 2) & 3, 1); } if (j + 3 < NT) { SLOAD(0, (j + 3) * KVBLK); } SBAR();
;     pv_d0(o, vb0 + ((j - 1) & 3) * SHM_V, pa0, pa1, pa2, pa3); partialSM<false>(pB0, pB1, mref, negm, alB);
;     RESC(alB); ABAR();
.Lattn_f4:
	s_add_i32 s41, s89, 0xffff4000
	s_and_b32 s41, s41, 0xc000
	s_add_i32 s42, s85, s41
	ds_read_b128 v[48:51], v243 offset:16384
	ds_read_b128 v[52:55], v243 offset:24576
	s_waitcnt lgkmcnt(1)
	v_mfma_f32_32x32x16_bf16 v[96:111], v[48:51], v[132:135], v[32:47]
	ds_read_b128 v[48:51], v244 offset:16384
	ds_read_b128 v[56:59], v244 offset:24576
	v_exp_f32_e32 v64, v64
	v_exp_f32_e32 v65, v65
	v_exp_f32_e32 v66, v66
	v_exp_f32_e32 v67, v67
	v_exp_f32_e32 v68, v68
	s_waitcnt lgkmcnt(2)
	v_mfma_f32_32x32x16_bf16 v[80:95], v[52:55], v[132:135], v[32:47]
	ds_read_b128 v[52:55], v245 offset:16384
	ds_read_b128 v[60:63], v245 offset:24576
	ds_read_b128 v[220:223], v246 offset:16384
	ds_read_b128 v[224:227], v246 offset:24576
	ds_read_b128 v[228:231], v247 offset:16384
	ds_read_b128 v[232:235], v247 offset:24576
	v_exp_f32_e32 v69, v69
	v_exp_f32_e32 v70, v70
	v_exp_f32_e32 v71, v71
	v_exp_f32_e32 v72, v72
	v_exp_f32_e32 v73, v73
	s_waitcnt lgkmcnt(7)
	v_mfma_f32_32x32x16_bf16 v[96:111], v[48:51], v[128:131], v[96:111]
	ds_read_b128 v[48:51], v248 offset:16384
	ds_read_b128 v[236:239], v248 offset:24576
	v_exp_f32_e32 v74, v74
	v_exp_f32_e32 v75, v75
	v_exp_f32_e32 v76, v76
	v_exp_f32_e32 v77, v77
	v_exp_f32_e32 v78, v78
	v_exp_f32_e32 v79, v79
	s_waitcnt lgkmcnt(8)
	v_mfma_f32_32x32x16_bf16 v[80:95], v[56:59], v[128:131], v[80:95]
	s_waitcnt lgkmcnt(7)
	v_mfma_f32_32x32x16_bf16 v[96:111], v[52:55], v[124:127], v[96:111]
	v_fma_f32 v52, v163, v152, v194
	v_add_f32_e32 v52, v216, v52
	v_add_f32_e32 v52, v192, v52
	v_add_f32_e32 v52, v195, v52
	v_add_f32_e32 v52, v190, v52
	v_add_f32_e32 v52, v193, v52
	v_add_f32_e32 v52, v189, v52
	s_waitcnt lgkmcnt(6)
	v_mfma_f32_32x32x16_bf16 v[80:95], v[60:63], v[124:127], v[80:95]
	v_add_f32_e32 v52, v191, v52
	v_add_f32_e32 v52, v186, v52
	v_add_f32_e32 v52, v188, v52
	v_add_f32_e32 v52, v185, v52
	v_add_f32_e32 v52, v187, v52
	v_add_f32_e32 v52, v181, v52
	v_add_f32_e32 v52, v183, v52
	s_waitcnt lgkmcnt(5)
	v_mfma_f32_32x32x16_bf16 v[96:111], v[220:223], v[120:123], v[96:111]
	v_add_f32_e32 v52, v180, v52
	v_add_f32_e32 v52, v182, v52
	v_add_f32_e32 v52, v64, v52
	v_add_f32_e32 v52, v65, v52
	v_add_f32_e32 v52, v66, v52
	v_add_f32_e32 v52, v67, v52
	v_add_f32_e32 v52, v68, v52
	s_waitcnt lgkmcnt(4)
	v_mfma_f32_32x32x16_bf16 v[80:95], v[224:227], v[120:123], v[80:95]
	v_add_f32_e32 v52, v69, v52
	v_add_f32_e32 v52, v70, v52
	v_add_f32_e32 v52, v71, v52
	v_add_f32_e32 v52, v72, v52
	v_add_f32_e32 v52, v73, v52
	v_add_f32_e32 v52, v74, v52
	v_add_f32_e32 v52, v75, v52
	s_waitcnt lgkmcnt(3)
	v_mfma_f32_32x32x16_bf16 v[96:111], v[228:231], v[116:119], v[96:111]
	v_add_f32_e32 v52, v76, v52
	v_add_f32_e32 v52, v77, v52
	v_add_f32_e32 v52, v78, v52
	v_add_f32_e32 v165, v79, v52
	s_waitcnt lgkmcnt(2)
	v_mfma_f32_32x32x16_bf16 v[80:95], v[232:235], v[116:119], v[80:95]
	v_cvt_pk_bf16_f32 v60, v194, v216
	v_cvt_pk_bf16_f32 v61, v192, v195
	v_cvt_pk_bf16_f32 v62, v190, v193
	v_cvt_pk_bf16_f32 v63, v189, v191
	v_cvt_pk_bf16_f32 v56, v186, v188
	v_cvt_pk_bf16_f32 v57, v185, v187
	v_cvt_pk_bf16_f32 v58, v181, v183
	s_waitcnt lgkmcnt(1)
	v_mfma_f32_32x32x16_bf16 v[96:111], v[48:51], v[112:115], v[96:111]
	v_cvt_pk_bf16_f32 v59, v180, v182
	v_cvt_pk_bf16_f32 v52, v64, v65
	v_cvt_pk_bf16_f32 v53, v66, v67
	v_cvt_pk_bf16_f32 v54, v68, v69
	v_cvt_pk_bf16_f32 v55, v70, v71
	v_cvt_pk_bf16_f32 v48, v72, v73
	v_cvt_pk_bf16_f32 v49, v74, v75
	s_waitcnt lgkmcnt(0)
	v_mfma_f32_32x32x16_bf16 v[80:95], v[236:239], v[112:115], v[80:95]
	v_cvt_pk_bf16_f32 v50, v76, v77
	v_cvt_pk_bf16_f32 v51, v78, v79
	s_add_i32 s42, s89, 0xffffc000
	s_and_b32 s42, s42, 0xc000
	s_add_i32 s43, s85, s42
	s_and_b64 vcc, exec, s[42:43]
	s_waitcnt vmcnt(2)
	ds_write_b128 v204, v[144:147] offset:49152
	s_waitcnt vmcnt(1)
	ds_write_b128 v249, v[148:151] offset:49152
	s_waitcnt vmcnt(0)
	ds_write_b64 v250, v[174:175] offset:49152
	global_load_dwordx4 v[136:139], v240, s[98:99]
	global_load_dwordx4 v[140:143], v241, s[98:99]
	global_load_dwordx2 v[172:173], v242, s[100:101]
	s_add_u32 s98, s98, 0x10000
	s_addc_u32 s99, s99, 0
	s_add_u32 s100, s100, 0x1000
	s_addc_u32 s101, s101, 0
.Lf1_741:
	s_and_b32 s48, s89, 0xc000
	ds_read_b64_tr_b16 v[64:65], v203
	ds_read_b64_tr_b16 v[66:67], v203 offset:2048
	ds_read_b64_tr_b16 v[70:71], v203 offset:2560
	ds_read_b64_tr_b16 v[68:69], v203 offset:512
	s_waitcnt lgkmcnt(2)
	v_mfma_f32_32x32x16_bf16 v[0:15], v[60:63], v[64:67], v[0:15]
	ds_read_b64_tr_b16 v[64:65], v203 offset:4096
	ds_read_b64_tr_b16 v[66:67], v203 offset:6144
	ds_read_b64_tr_b16 v[74:75], v203 offset:6656
	ds_read_b64_tr_b16 v[72:73], v203 offset:4608
	s_waitcnt lgkmcnt(2)
	v_mfma_f32_32x32x16_bf16 v[0:15], v[56:59], v[64:67], v[0:15]
	ds_read_b64_tr_b16 v[64:65], v203 offset:8192
	ds_read_b64_tr_b16 v[66:67], v203 offset:10240
	ds_read_b64_tr_b16 v[78:79], v203 offset:10752
	ds_read_b64_tr_b16 v[76:77], v203 offset:8704
	v_mfma_f32_32x32x16_bf16 v[16:31], v[60:63], v[68:71], v[16:31]
	s_waitcnt lgkmcnt(2)
	v_mfma_f32_32x32x16_bf16 v[0:15], v[52:55], v[64:67], v[0:15]
	ds_read_b64_tr_b16 v[64:65], v203 offset:12288
	ds_read_b64_tr_b16 v[66:67], v203 offset:14336
	ds_read_b64_tr_b16 v[186:187], v203 offset:14848
	ds_read_b64_tr_b16 v[184:185], v203 offset:12800
	v_mfma_f32_32x32x16_bf16 v[16:31], v[56:59], v[72:75], v[16:31]
	s_waitcnt lgkmcnt(2)
	v_mfma_f32_32x32x16_bf16 v[0:15], v[48:51], v[64:67], v[0:15]
	v_max_f32_e32 v64, v96, v97
	v_max3_f32 v64, v64, v98, v99
	v_max3_f32 v60, v64, v100, v101
	v_max3_f32 v60, v60, v102, v103
	v_max3_f32 v60, v60, v104, v105
	v_max3_f32 v60, v60, v106, v107
	v_max3_f32 v60, v60, v108, v109
	v_mfma_f32_32x32x16_bf16 v[16:31], v[52:55], v[76:79], v[16:31]
	v_max3_f32 v60, v60, v110, v111
	v_max3_f32 v60, v60, v80, v81
	v_max3_f32 v56, v60, v82, v83
	v_max3_f32 v56, v56, v84, v85
	v_max3_f32 v56, v56, v86, v87
	v_max3_f32 v56, v56, v88, v89
	v_max3_f32 v56, v56, v90, v91
	v_max3_f32 v56, v56, v92, v93
	s_waitcnt lgkmcnt(0)
	v_mfma_f32_32x32x16_bf16 v[16:31], v[48:51], v[184:187], v[16:31]
	v_max3_f32 v56, v56, v94, v95
	v_mov_b32_e32 v52, v56
	s_nop 1
	v_permlane32_swap_b32_e32 v56, v52
	v_max_f32_e32 v52, v56, v52
	v_cmp_ge_f32_e32 vcc, s86, v52
	s_cmp_eq_u64 vcc, exec
	s_cbranch_scc0 .Lf1_757
	v_mov_b32_e32 v169, 1.0
; #define SBAR() __builtin_amdgcn_sched_barrier(0)
; #define PK4(P, BASE, OUT) do { u32x4 w = {cvt_pk_bf16(P[BASE + 0], P[BASE + 1]), cvt_pk_bf16(P[BASE + 2], P[BASE + 3]), cvt_pk_bf16(P[BASE + 4], P[BASE + 5]), cvt_pk_bf16(P[BASE + 6], P[BASE + 7])}; \
;     OUT = *reinterpret_cast<bf16x8*>(&w); } while (0)
; #define ABAR() asm volatile("s_waitcnt lgkmcnt(0)\n\ts_barrier" ::: "memory")
; __device__ __forceinline__ void finishSM(f32x16& p0, f32x16& p1, float alpha, float& l_reg, bf16x8& pa0, bf16x8& pa1, bf16x8& pa2, bf16x8& pa3) {
; #pragma unroll
;   for (int r = 0; r < 16; ++r) p1[r] = __builtin_amdgcn_exp2f(p1[r]);
;   float ps = 0;
; #pragma unroll
;   for (int r = 0; r < 16; ++r) ps += p0[r];
; #pragma unroll
;   for (int r = 0; r < 16; ++r) ps += p1[r];
;   { auto rr = __builtin_amdgcn_permlane32_swap(__float_as_uint(ps), __float_as_uint(ps), false, false);
;     ps = __uint_as_float(rr[0]) + __uint_as_float(rr[1]); }
;   l_reg = l_reg * alpha + ps;
;     ...
;   PK4(p0, 0, pa0); PK4(p0, 8, pa1); PK4(p1, 0, pa2); PK4(p1, 8, pa3);
;     ...
; }
; __device__ __forceinline__ void qkt(f32x16& p0, f32x16& p1, const char* Ks, const bf16x8* qr, const f32x16& negm, int r32, int hi) {
;   p0 = negm; p1 = negm;
; #pragma unroll
;   for (int d0 = 0; d0 < 6; ++d0) { int cb = (d0 * 16 + hi * 8) * 2;
;     bf16x8 b0 = *reinterpret_cast<const bf16x8*>(Ks + KSWZ(r32, cb));
;     bf16x8 b1 = *reinterpret_cast<const bf16x8*>(Ks + KSWZ(32 + r32, cb));
;     p0 = __builtin_amdgcn_mfma_f32_32x32x16_bf16(b0, qr[d0], p0, 0, 0, 0);
;     p1 = __builtin_amdgcn_mfma_f32_32x32x16_bf16(b1, qr[d0], p1, 0, 0, 0); }
; }
; __device__ __forceinline__ void attn_unit(const bf16_t* __restrict__ Qb, const bf16_t* __restrict__ KNh, const bf16_t* __restrict__ KRb, const bf16_t* __restrict__ Vh, bf16_t* __restrict__ Ob, char* lds) {
;     ...
;     if (j + 2 < NT) { SWRITE((j + 2) & 3, 1); } if (j + 3 < NT) { SLOAD(0, (j + 3) * KVBLK); } SBAR();
;     pv_d0(o, vb0 + ((j - 1) & 3) * SHM_V, pa0, pa1, pa2, pa3); partialSM<false>(pB0, pB1, mref, negm, alB);
;     RESC(alB); ABAR();
;     SBAR(); qkt(pA0, pA1, K_lds + ((j + 1) & 3) * SHM_K, qr, negm, r32, hi);
;     finishSM(pB0, pB1, alB, l_reg, pa0, pa1, pa2, pa3); SBAR();
;     if (j + 3 < NT) { SWRITE((j + 3) & 3, 0); } if (j + 4 < NT) { SLOAD(1, (j + 4) * KVBLK); } SBAR();
.Lf1_746:
	s_waitcnt lgkmcnt(0)
	s_barrier
	v_exp_f32_e32 v192, v96
	v_exp_f32_e32 v193, v97
	v_exp_f32_e32 v194, v98
	v_exp_f32_e32 v195, v99
	v_exp_f32_e32 v216, v100
	v_exp_f32_e32 v217, v101
	v_exp_f32_e32 v219, v102
	v_exp_f32_e32 v220, v103
	v_exp_f32_e32 v221, v104
	v_exp_f32_e32 v222, v105
	v_exp_f32_e32 v223, v106
	v_exp_f32_e32 v224, v107
	v_exp_f32_e32 v225, v108
	v_exp_f32_e32 v226, v109
	v_exp_f32_e32 v227, v110
	v_exp_f32_e32 v228, v111
	s_add_i32 s46, s89, 0xffff8000
	s_and_b32 s46, s46, 0xc000
	s_add_i32 s46, s46, 0
	s_add_i32 s46, s46, 0x10000
	ds_read_b128 v[64:67], v243 offset:32768
	ds_read_b128 v[184:187], v243 offset:40960
	v_exp_f32_e32 v80, v80
	v_exp_f32_e32 v81, v81
	s_waitcnt lgkmcnt(1)
	v_mfma_f32_32x32x16_bf16 v[96:111], v[64:67], v[132:135], v[32:47]
	v_exp_f32_e32 v82, v82
	v_exp_f32_e32 v83, v83
	v_exp_f32_e32 v87, v87
	v_exp_f32_e32 v229, v92
	v_exp_f32_e32 v230, v93
	v_exp_f32_e32 v231, v94
	v_exp_f32_e32 v232, v95
	s_waitcnt lgkmcnt(0)
	v_mfma_f32_32x32x16_bf16 v[64:79], v[184:187], v[132:135], v[32:47]
	ds_read_b128 v[184:187], v244 offset:32768
	ds_read_b128 v[188:191], v244 offset:40960
	s_waitcnt lgkmcnt(1)
	v_mfma_f32_32x32x16_bf16 v[96:111], v[184:187], v[128:131], v[96:111]
	s_waitcnt lgkmcnt(0)
	v_mfma_f32_32x32x16_bf16 v[64:79], v[188:191], v[128:131], v[64:79]
	ds_read_b128 v[184:187], v245 offset:32768
	ds_read_b128 v[188:191], v245 offset:40960
	s_waitcnt lgkmcnt(1)
	v_mfma_f32_32x32x16_bf16 v[96:111], v[184:187], v[124:127], v[96:111]
	s_waitcnt lgkmcnt(0)
	v_mfma_f32_32x32x16_bf16 v[64:79], v[188:191], v[124:127], v[64:79]
	ds_read_b128 v[184:187], v246 offset:32768
	ds_read_b128 v[188:191], v246 offset:40960
	s_waitcnt lgkmcnt(1)
	v_mfma_f32_32x32x16_bf16 v[96:111], v[184:187], v[120:123], v[96:111]
	s_waitcnt lgkmcnt(0)
	v_mfma_f32_32x32x16_bf16 v[64:79], v[188:191], v[120:123], v[64:79]
	ds_read_b128 v[184:187], v247 offset:32768
	ds_read_b128 v[188:191], v247 offset:40960
	s_waitcnt lgkmcnt(1)
	v_mfma_f32_32x32x16_bf16 v[96:111], v[184:187], v[116:119], v[96:111]
	s_waitcnt lgkmcnt(0)
	v_mfma_f32_32x32x16_bf16 v[64:79], v[188:191], v[116:119], v[64:79]
	ds_read_b128 v[184:187], v248 offset:32768
	ds_read_b128 v[188:191], v248 offset:40960
	v_cvt_pk_bf16_f32 v92, v192, v193
	v_cvt_pk_bf16_f32 v93, v194, v195
	v_cvt_pk_bf16_f32 v94, v216, v217
	v_cvt_pk_bf16_f32 v95, v219, v220
	s_waitcnt lgkmcnt(1)
	v_mfma_f32_32x32x16_bf16 v[96:111], v[184:187], v[112:115], v[96:111]
	v_exp_f32_e32 v185, v84
	v_fma_f32 v84, v165, v169, v192
	v_add_f32_e32 v84, v193, v84
	v_add_f32_e32 v84, v194, v84
	v_add_f32_e32 v84, v195, v84
	v_add_f32_e32 v84, v216, v84
	v_add_f32_e32 v84, v217, v84
	v_add_f32_e32 v84, v219, v84
	v_add_f32_e32 v84, v220, v84
	v_add_f32_e32 v84, v221, v84
	v_add_f32_e32 v84, v222, v84
	v_add_f32_e32 v84, v223, v84
	v_add_f32_e32 v84, v224, v84
	v_add_f32_e32 v84, v225, v84
	v_add_f32_e32 v84, v226, v84
	v_add_f32_e32 v84, v227, v84
	v_add_f32_e32 v84, v228, v84
	v_add_f32_e32 v84, v80, v84
	v_exp_f32_e32 v186, v85
	v_add_f32_e32 v84, v81, v84
	v_exp_f32_e32 v187, v86
	v_add_f32_e32 v84, v82, v84
	v_add_f32_e32 v84, v83, v84
	s_waitcnt lgkmcnt(0)
	v_mfma_f32_32x32x16_bf16 v[64:79], v[188:191], v[112:115], v[64:79]
	v_exp_f32_e32 v188, v88
	v_add_f32_e32 v84, v185, v84
	v_exp_f32_e32 v189, v89
	v_add_f32_e32 v84, v186, v84
	v_exp_f32_e32 v190, v90
	v_add_f32_e32 v84, v187, v84
	v_exp_f32_e32 v191, v91
	v_add_f32_e32 v84, v87, v84
	v_add_f32_e32 v84, v188, v84
	v_add_f32_e32 v84, v189, v84
	v_add_f32_e32 v84, v190, v84
	v_add_f32_e32 v84, v191, v84
	v_add_f32_e32 v84, v229, v84
	v_add_f32_e32 v84, v230, v84
	v_add_f32_e32 v84, v231, v84
	v_add_f32_e32 v152, v232, v84
	v_cvt_pk_bf16_f32 v88, v221, v222
	v_cvt_pk_bf16_f32 v89, v223, v224
	v_cvt_pk_bf16_f32 v90, v225, v226
	v_cvt_pk_bf16_f32 v91, v227, v228
	v_cvt_pk_bf16_f32 v84, v80, v81
	v_cvt_pk_bf16_f32 v85, v82, v83
	v_cvt_pk_bf16_f32 v86, v185, v186
	v_cvt_pk_bf16_f32 v87, v187, v87
	v_cvt_pk_bf16_f32 v80, v188, v189
	v_cvt_pk_bf16_f32 v81, v190, v191
	v_cvt_pk_bf16_f32 v82, v229, v230
	v_cvt_pk_bf16_f32 v83, v231, v232
	s_add_i32 s44, s48, 0
	s_add_i32 s44, s44, 0x10000
	s_waitcnt vmcnt(2)
	ds_write_b128 v204, v[136:139]
	s_waitcnt vmcnt(1)
	ds_write_b128 v249, v[140:143]
	s_waitcnt vmcnt(0)
	ds_write_b64 v250, v[172:173]
.Lf1_748:
	global_load_dwordx4 v[144:147], v240, s[98:99]
	global_load_dwordx4 v[148:151], v241, s[98:99]
	global_load_dwordx2 v[174:175], v242, s[100:101]
	s_add_u32 s98, s98, 0x10000
	s_addc_u32 s99, s99, 0
	s_add_u32 s100, s100, 0x1000
	s_addc_u32 s101, s101, 0
; template <bool FIRST> __device__ __forceinline__ void partialSM(f32x16& p0, f32x16& p1, float& mref, f32x16& negm, float& alpha) {
;   constexpr float THRL = THR * 1.4426950408889634f;
;   float pmax = p0[0];
; #pragma unroll
;   for (int r = 1; r < 16; ++r) pmax = fmaxf(pmax, p0[r]);
; #pragma unroll
;   for (int r = 0; r < 16; ++r) pmax = fmaxf(pmax, p1[r]);
;   { auto rr = __builtin_amdgcn_permlane32_swap(__float_as_uint(pmax), __float_as_uint(pmax), false, false);
;     pmax = fmaxf(__uint_as_float(rr[0]), __uint_as_float(rr[1])); }
;   if (!FIRST && __builtin_expect(__all(pmax <= THRL), 1)) { alpha = 1.f; }
;   else { const float dl = FIRST ? pmax : fmaxf(pmax, 0.f); mref += dl; alpha = FIRST ? 1.f : __builtin_amdgcn_exp2f(-dl);
; #pragma unroll
;     for (int r = 0; r < 16; ++r) { p0[r] -= dl; p1[r] -= dl; }
;     const float nm = -mref;
; #pragma unroll
;     for (int r = 0; r < 16; ++r) negm[r] = nm; }
; #pragma unroll
;   for (int r = 0; r < 16; ++r) p0[r] = __builtin_amdgcn_exp2f(p0[r]);
; }
; __device__ __forceinline__ void finishSM(f32x16& p0, f32x16& p1, float alpha, float& l_reg, bf16x8& pa0, bf16x8& pa1, bf16x8& pa2, bf16x8& pa3) {
; #pragma unroll
;   for (int r = 0; r < 16; ++r) p1[r] = __builtin_amdgcn_exp2f(p1[r]);
;   float ps = 0;
; #pragma unroll
;   for (int r = 0; r < 16; ++r) ps += p0[r];
; #pragma unroll
;   for (int r = 0; r < 16; ++r) ps += p1[r];
;   { auto rr = __builtin_amdgcn_permlane32_swap(__float_as_uint(ps), __float_as_uint(ps), false, false);
;     ps = __uint_as_float(rr[0]) + __uint_as_float(rr[1]); }
;   l_reg = l_reg * alpha + ps;
;     ...
;   PK4(p0, 0, pa0); PK4(p0, 8, pa1); PK4(p1, 0, pa2); PK4(p1, 8, pa3);
;     ...
; }
; __device__ __forceinline__ void qkt(f32x16& p0, f32x16& p1, const char* Ks, const bf16x8* qr, const f32x16& negm, int r32, int hi) {
;   p0 = negm; p1 = negm;
; #pragma unroll
;   for (int d0 = 0; d0 < 6; ++d0) { int cb = (d0 * 16 + hi * 8) * 2;
;     bf16x8 b0 = *reinterpret_cast<const bf16x8*>(Ks + KSWZ(r32, cb));
;     bf16x8 b1 = *reinterpret_cast<const bf16x8*>(Ks + KSWZ(32 + r32, cb));
;     p0 = __builtin_amdgcn_mfma_f32_32x32x16_bf16(b0, qr[d0], p0, 0, 0, 0);
;     p1 = __builtin_amdgcn_mfma_f32_32x32x16_bf16(b1, qr[d0], p1, 0, 0, 0); }
; }
; template <int D0> __device__ __forceinline__ void pv_one(f32x16& od, lds_cptr vp, bf16x8 pa0, bf16x8 pa1, bf16x8 pa2, bf16x8 pa3) {
.Lf1_750:
	ds_read_b64_tr_b16 v[180:181], v203 offset:16384
	ds_read_b64_tr_b16 v[182:183], v203 offset:18432
	ds_read_b64_tr_b16 v[188:189], v203 offset:18944
	ds_read_b64_tr_b16 v[186:187], v203 offset:16896
	s_waitcnt lgkmcnt(2)
	v_mfma_f32_32x32x16_bf16 v[0:15], v[92:95], v[180:183], v[0:15]
	ds_read_b64_tr_b16 v[180:181], v203 offset:20480
	ds_read_b64_tr_b16 v[182:183], v203 offset:22528
	ds_read_b64_tr_b16 v[192:193], v203 offset:23040
	ds_read_b64_tr_b16 v[190:191], v203 offset:20992
	s_waitcnt lgkmcnt(2)
	v_mfma_f32_32x32x16_bf16 v[0:15], v[88:91], v[180:183], v[0:15]
	ds_read_b64_tr_b16 v[180:181], v203 offset:24576
	ds_read_b64_tr_b16 v[182:183], v203 offset:26624
	ds_read_b64_tr_b16 v[222:223], v203 offset:27136
	ds_read_b64_tr_b16 v[220:221], v203 offset:25088
	v_mfma_f32_32x32x16_bf16 v[16:31], v[92:95], v[186:189], v[16:31]
	s_waitcnt lgkmcnt(2)
	v_mfma_f32_32x32x16_bf16 v[0:15], v[84:87], v[180:183], v[0:15]
	ds_read_b64_tr_b16 v[180:181], v203 offset:28672
	ds_read_b64_tr_b16 v[182:183], v203 offset:30720
	ds_read_b64_tr_b16 v[226:227], v203 offset:31232
	ds_read_b64_tr_b16 v[224:225], v203 offset:29184
	v_mfma_f32_32x32x16_bf16 v[16:31], v[88:91], v[190:193], v[16:31]
	s_waitcnt lgkmcnt(2)
	v_mfma_f32_32x32x16_bf16 v[0:15], v[80:83], v[180:183], v[0:15]
	v_max_f32_e32 v180, v96, v97
	v_max3_f32 v180, v180, v98, v99
	v_max3_f32 v180, v180, v100, v101
	v_max3_f32 v92, v180, v102, v103
	v_max3_f32 v92, v92, v104, v105
	v_max3_f32 v92, v92, v106, v107
	v_max3_f32 v92, v92, v108, v109
	v_mfma_f32_32x32x16_bf16 v[16:31], v[84:87], v[220:223], v[16:31]
	v_max3_f32 v92, v92, v110, v111
	v_max3_f32 v92, v92, v64, v65
	v_max3_f32 v92, v92, v66, v67
	v_max3_f32 v88, v92, v68, v69
	v_max3_f32 v88, v88, v70, v71
	v_max3_f32 v88, v88, v72, v73
	v_max3_f32 v88, v88, v74, v75
	v_max3_f32 v88, v88, v76, v77
	s_waitcnt lgkmcnt(0)
	v_mfma_f32_32x32x16_bf16 v[16:31], v[80:83], v[224:227], v[16:31]
	v_max3_f32 v88, v88, v78, v79
	v_mov_b32_e32 v89, v88
	s_nop 1
	v_permlane32_swap_b32_e32 v88, v89
	v_max_f32_e32 v85, v88, v89
	v_cmp_ge_f32_e32 vcc, s86, v85
	s_cmp_eq_u64 vcc, exec
	v_mov_b32_e32 v84, 1.0
	s_cbranch_scc0 .Lf1_758
.Lf1_755:
	v_exp_f32_e32 v194, v96
	v_exp_f32_e32 v216, v97
	v_exp_f32_e32 v192, v98
	v_exp_f32_e32 v195, v99
	v_exp_f32_e32 v190, v100
	v_exp_f32_e32 v193, v101
	v_exp_f32_e32 v189, v102
	v_exp_f32_e32 v191, v103
	v_exp_f32_e32 v186, v104
	v_exp_f32_e32 v188, v105
	v_exp_f32_e32 v185, v106
	v_exp_f32_e32 v187, v107
	v_exp_f32_e32 v181, v108
	v_exp_f32_e32 v183, v109
	v_exp_f32_e32 v180, v110
	v_exp_f32_e32 v182, v111
	s_waitcnt lgkmcnt(0)
	s_barrier
	s_add_i32 s90, s90, 2
	s_add_i32 s89, s89, 0x8000
	v_mov_b32_e32 v163, v84
	s_add_i32 s41, s89, 0xffff4000
	s_and_b32 s41, s41, 0xc000
	s_add_i32 s42, s85, s41
	ds_read_b128 v[48:51], v243 offset:49152
	ds_read_b128 v[52:55], v243 offset:57344
	s_waitcnt lgkmcnt(1)
	v_mfma_f32_32x32x16_bf16 v[96:111], v[48:51], v[132:135], v[32:47]
	ds_read_b128 v[48:51], v244 offset:49152
	ds_read_b128 v[56:59], v244 offset:57344
	v_exp_f32_e32 v64, v64
	v_exp_f32_e32 v65, v65
	v_exp_f32_e32 v66, v66
	v_exp_f32_e32 v67, v67
	v_exp_f32_e32 v68, v68
	s_waitcnt lgkmcnt(2)
	v_mfma_f32_32x32x16_bf16 v[80:95], v[52:55], v[132:135], v[32:47]
	ds_read_b128 v[52:55], v245 offset:49152
	ds_read_b128 v[60:63], v245 offset:57344
	ds_read_b128 v[220:223], v246 offset:49152
	ds_read_b128 v[224:227], v246 offset:57344
	ds_read_b128 v[228:231], v247 offset:49152
	ds_read_b128 v[232:235], v247 offset:57344
	v_exp_f32_e32 v69, v69
	v_exp_f32_e32 v70, v70
	v_exp_f32_e32 v71, v71
	v_exp_f32_e32 v72, v72
	v_exp_f32_e32 v73, v73
	s_waitcnt lgkmcnt(7)
	v_mfma_f32_32x32x16_bf16 v[96:111], v[48:51], v[128:131], v[96:111]
	ds_read_b128 v[48:51], v248 offset:49152
	ds_read_b128 v[236:239], v248 offset:57344
	v_exp_f32_e32 v74, v74
	v_exp_f32_e32 v75, v75
	v_exp_f32_e32 v76, v76
	v_exp_f32_e32 v77, v77
	v_exp_f32_e32 v78, v78
	v_exp_f32_e32 v79, v79
	s_waitcnt lgkmcnt(8)
	v_mfma_f32_32x32x16_bf16 v[80:95], v[56:59], v[128:131], v[80:95]
	s_waitcnt lgkmcnt(7)
	v_mfma_f32_32x32x16_bf16 v[96:111], v[52:55], v[124:127], v[96:111]
	v_fma_f32 v52, v163, v152, v194
	v_add_f32_e32 v52, v216, v52
	v_add_f32_e32 v52, v192, v52
	v_add_f32_e32 v52, v195, v52
	v_add_f32_e32 v52, v190, v52
	v_add_f32_e32 v52, v193, v52
	v_add_f32_e32 v52, v189, v52
	s_waitcnt lgkmcnt(6)
	v_mfma_f32_32x32x16_bf16 v[80:95], v[60:63], v[124:127], v[80:95]
	v_add_f32_e32 v52, v191, v52
	v_add_f32_e32 v52, v186, v52
	v_add_f32_e32 v52, v188, v52
	v_add_f32_e32 v52, v185, v52
	v_add_f32_e32 v52, v187, v52
	v_add_f32_e32 v52, v181, v52
	v_add_f32_e32 v52, v183, v52
	s_waitcnt lgkmcnt(5)
	v_mfma_f32_32x32x16_bf16 v[96:111], v[220:223], v[120:123], v[96:111]
	v_add_f32_e32 v52, v180, v52
	v_add_f32_e32 v52, v182, v52
	v_add_f32_e32 v52, v64, v52
	v_add_f32_e32 v52, v65, v52
	v_add_f32_e32 v52, v66, v52
	v_add_f32_e32 v52, v67, v52
	v_add_f32_e32 v52, v68, v52
	s_waitcnt lgkmcnt(4)
	v_mfma_f32_32x32x16_bf16 v[80:95], v[224:227], v[120:123], v[80:95]
	v_add_f32_e32 v52, v69, v52
	v_add_f32_e32 v52, v70, v52
	v_add_f32_e32 v52, v71, v52
	v_add_f32_e32 v52, v72, v52
	v_add_f32_e32 v52, v73, v52
	v_add_f32_e32 v52, v74, v52
	v_add_f32_e32 v52, v75, v52
	s_waitcnt lgkmcnt(3)
	v_mfma_f32_32x32x16_bf16 v[96:111], v[228:231], v[116:119], v[96:111]
	v_add_f32_e32 v52, v76, v52
	v_add_f32_e32 v52, v77, v52
	v_add_f32_e32 v52, v78, v52
	v_add_f32_e32 v165, v79, v52
	s_waitcnt lgkmcnt(2)
	v_mfma_f32_32x32x16_bf16 v[80:95], v[232:235], v[116:119], v[80:95]
	v_cvt_pk_bf16_f32 v60, v194, v216
	v_cvt_pk_bf16_f32 v61, v192, v195
	v_cvt_pk_bf16_f32 v62, v190, v193
	v_cvt_pk_bf16_f32 v63, v189, v191
	v_cvt_pk_bf16_f32 v56, v186, v188
	v_cvt_pk_bf16_f32 v57, v185, v187
	v_cvt_pk_bf16_f32 v58, v181, v183
	s_waitcnt lgkmcnt(1)
	v_mfma_f32_32x32x16_bf16 v[96:111], v[48:51], v[112:115], v[96:111]
	v_cvt_pk_bf16_f32 v59, v180, v182
	v_cvt_pk_bf16_f32 v52, v64, v65
	v_cvt_pk_bf16_f32 v53, v66, v67
	v_cvt_pk_bf16_f32 v54, v68, v69
	v_cvt_pk_bf16_f32 v55, v70, v71
	v_cvt_pk_bf16_f32 v48, v72, v73
	v_cvt_pk_bf16_f32 v49, v74, v75
	s_waitcnt lgkmcnt(0)
	v_mfma_f32_32x32x16_bf16 v[80:95], v[236:239], v[112:115], v[80:95]
	v_cvt_pk_bf16_f32 v50, v76, v77
	v_cvt_pk_bf16_f32 v51, v78, v79
	s_add_i32 s42, s89, 0xffffc000
	s_and_b32 s42, s42, 0xc000
	s_add_i32 s43, s85, s42
	s_and_b64 vcc, exec, s[42:43]
	s_waitcnt vmcnt(2)
	ds_write_b128 v204, v[144:147] offset:16384
	s_waitcnt vmcnt(1)
	ds_write_b128 v249, v[148:151] offset:16384
	s_waitcnt vmcnt(0)
	ds_write_b64 v250, v[174:175] offset:16384
	global_load_dwordx4 v[136:139], v240, s[98:99]
	global_load_dwordx4 v[140:143], v241, s[98:99]
	global_load_dwordx2 v[172:173], v242, s[100:101]
	s_add_u32 s98, s98, 0x10000
	s_addc_u32 s99, s99, 0
	s_add_u32 s100, s100, 0x1000
	s_addc_u32 s101, s101, 0
; template <bool FIRST> __device__ __forceinline__ void partialSM(f32x16& p0, f32x16& p1, float& mref, f32x16& negm, float& alpha) {
;   constexpr float THRL = THR * 1.4426950408889634f;
;   float pmax = p0[0];
; #pragma unroll
;   for (int r = 1; r < 16; ++r) pmax = fmaxf(pmax, p0[r]);
; #pragma unroll
;   for (int r = 0; r < 16; ++r) pmax = fmaxf(pmax, p1[r]);
;   { auto rr = __builtin_amdgcn_permlane32_swap(__float_as_uint(pmax), __float_as_uint(pmax), false, false);
;     pmax = fmaxf(__uint_as_float(rr[0]), __uint_as_float(rr[1])); }
;   if (!FIRST && __builtin_expect(__all(pmax <= THRL), 1)) { alpha = 1.f; }
;   else { const float dl = FIRST ? pmax : fmaxf(pmax, 0.f); mref += dl; alpha = FIRST ? 1.f : __builtin_amdgcn_exp2f(-dl);
; #pragma unroll
;     for (int r = 0; r < 16; ++r) { p0[r] -= dl; p1[r] -= dl; }
;     const float nm = -mref;
; #pragma unroll
;     for (int r = 0; r < 16; ++r) negm[r] = nm; }
; #pragma unroll
;   for (int r = 0; r < 16; ++r) p0[r] = __builtin_amdgcn_exp2f(p0[r]);
; }
; __device__ __forceinline__ void finishSM(f32x16& p0, f32x16& p1, float alpha, float& l_reg, bf16x8& pa0, bf16x8& pa1, bf16x8& pa2, bf16x8& pa3) {
; #pragma unroll
;   for (int r = 0; r < 16; ++r) p1[r] = __builtin_amdgcn_exp2f(p1[r]);
;   float ps = 0;
; #pragma unroll
;   for (int r = 0; r < 16; ++r) ps += p0[r];
; #pragma unroll
;   for (int r = 0; r < 16; ++r) ps += p1[r];
;   { auto rr = __builtin_amdgcn_permlane32_swap(__float_as_uint(ps), __float_as_uint(ps), false, false);
;     ps = __uint_as_float(rr[0]) + __uint_as_float(rr[1]); }
;   l_reg = l_reg * alpha + ps;
;     ...
;   PK4(p0, 0, pa0); PK4(p0, 8, pa1); PK4(p1, 0, pa2); PK4(p1, 8, pa3);
;     ...
; }
; __device__ __forceinline__ void qkt(f32x16& p0, f32x16& p1, const char* Ks, const bf16x8* qr, const f32x16& negm, int r32, int hi) {
;   p0 = negm; p1 = negm;
; #pragma unroll
;   for (int d0 = 0; d0 < 6; ++d0) { int cb = (d0 * 16 + hi * 8) * 2;
;     bf16x8 b0 = *reinterpret_cast<const bf16x8*>(Ks + KSWZ(r32, cb));
;     bf16x8 b1 = *reinterpret_cast<const bf16x8*>(Ks + KSWZ(32 + r32, cb));
;     p0 = __builtin_amdgcn_mfma_f32_32x32x16_bf16(b0, qr[d0], p0, 0, 0, 0);
;     p1 = __builtin_amdgcn_mfma_f32_32x32x16_bf16(b1, qr[d0], p1, 0, 0, 0); }
; }
; template <int D0> __device__ __forceinline__ void pv_one(f32x16& od, lds_cptr vp, bf16x8 pa0, bf16x8 pa1, bf16x8 pa2, bf16x8 pa3) {
.Lf2_741:
	s_and_b32 s48, s89, 0xc000
	ds_read_b64_tr_b16 v[64:65], v203 offset:32768
	ds_read_b64_tr_b16 v[66:67], v203 offset:34816
	ds_read_b64_tr_b16 v[70:71], v203 offset:35328
	ds_read_b64_tr_b16 v[68:69], v203 offset:33280
	s_waitcnt lgkmcnt(2)
	v_mfma_f32_32x32x16_bf16 v[0:15], v[60:63], v[64:67], v[0:15]
	ds_read_b64_tr_b16 v[64:65], v203 offset:36864
	ds_read_b64_tr_b16 v[66:67], v203 offset:38912
	ds_read_b64_tr_b16 v[74:75], v203 offset:39424
	ds_read_b64_tr_b16 v[72:73], v203 offset:37376
	s_waitcnt lgkmcnt(2)
	v_mfma_f32_32x32x16_bf16 v[0:15], v[56:59], v[64:67], v[0:15]
	ds_read_b64_tr_b16 v[64:65], v203 offset:40960
	ds_read_b64_tr_b16 v[66:67], v203 offset:43008
	ds_read_b64_tr_b16 v[78:79], v203 offset:43520
	ds_read_b64_tr_b16 v[76:77], v203 offset:41472
	v_mfma_f32_32x32x16_bf16 v[16:31], v[60:63], v[68:71], v[16:31]
	s_waitcnt lgkmcnt(2)
	v_mfma_f32_32x32x16_bf16 v[0:15], v[52:55], v[64:67], v[0:15]
	ds_read_b64_tr_b16 v[64:65], v203 offset:45056
	ds_read_b64_tr_b16 v[66:67], v203 offset:47104
	ds_read_b64_tr_b16 v[186:187], v203 offset:47616
	ds_read_b64_tr_b16 v[184:185], v203 offset:45568
	v_mfma_f32_32x32x16_bf16 v[16:31], v[56:59], v[72:75], v[16:31]
	s_waitcnt lgkmcnt(2)
	v_mfma_f32_32x32x16_bf16 v[0:15], v[48:51], v[64:67], v[0:15]
	v_max_f32_e32 v64, v96, v97
	v_max3_f32 v64, v64, v98, v99
	v_max3_f32 v60, v64, v100, v101
	v_max3_f32 v60, v60, v102, v103
	v_max3_f32 v60, v60, v104, v105
	v_max3_f32 v60, v60, v106, v107
	v_max3_f32 v60, v60, v108, v109
	v_mfma_f32_32x32x16_bf16 v[16:31], v[52:55], v[76:79], v[16:31]
	v_max3_f32 v60, v60, v110, v111
	v_max3_f32 v60, v60, v80, v81
	v_max3_f32 v56, v60, v82, v83
	v_max3_f32 v56, v56, v84, v85
	v_max3_f32 v56, v56, v86, v87
	v_max3_f32 v56, v56, v88, v89
	v_max3_f32 v56, v56, v90, v91
	v_max3_f32 v56, v56, v92, v93
	s_waitcnt lgkmcnt(0)
	v_mfma_f32_32x32x16_bf16 v[16:31], v[48:51], v[184:187], v[16:31]
	v_max3_f32 v56, v56, v94, v95
	v_mov_b32_e32 v52, v56
	s_nop 1
	v_permlane32_swap_b32_e32 v56, v52
	v_max_f32_e32 v52, v56, v52
	v_cmp_ge_f32_e32 vcc, s86, v52
	s_cmp_eq_u64 vcc, exec
	s_cbranch_scc0 .Lf2_757
	v_mov_b32_e32 v169, 1.0
.Lf2_746:
	s_waitcnt lgkmcnt(0)
	s_barrier
	v_exp_f32_e32 v192, v96
	v_exp_f32_e32 v193, v97
	v_exp_f32_e32 v194, v98
	v_exp_f32_e32 v195, v99
	v_exp_f32_e32 v216, v100
	v_exp_f32_e32 v217, v101
	v_exp_f32_e32 v219, v102
	v_exp_f32_e32 v220, v103
	v_exp_f32_e32 v221, v104
	v_exp_f32_e32 v222, v105
	v_exp_f32_e32 v223, v106
	v_exp_f32_e32 v224, v107
	v_exp_f32_e32 v225, v108
	v_exp_f32_e32 v226, v109
	v_exp_f32_e32 v227, v110
	v_exp_f32_e32 v228, v111
	s_add_i32 s46, s89, 0xffff8000
	s_and_b32 s46, s46, 0xc000
	s_add_i32 s46, s46, 0
	s_add_i32 s46, s46, 0x10000
	ds_read_b128 v[64:67], v243
	ds_read_b128 v[184:187], v243 offset:8192
	v_exp_f32_e32 v80, v80
	v_exp_f32_e32 v81, v81
	s_waitcnt lgkmcnt(1)
	v_mfma_f32_32x32x16_bf16 v[96:111], v[64:67], v[132:135], v[32:47]
	v_exp_f32_e32 v82, v82
	v_exp_f32_e32 v83, v83
	v_exp_f32_e32 v87, v87
	v_exp_f32_e32 v229, v92
	v_exp_f32_e32 v230, v93
	v_exp_f32_e32 v231, v94
	v_exp_f32_e32 v232, v95
	s_waitcnt lgkmcnt(0)
	v_mfma_f32_32x32x16_bf16 v[64:79], v[184:187], v[132:135], v[32:47]
	ds_read_b128 v[184:187], v244
	ds_read_b128 v[188:191], v244 offset:8192
	s_waitcnt lgkmcnt(1)
	v_mfma_f32_32x32x16_bf16 v[96:111], v[184:187], v[128:131], v[96:111]
	s_waitcnt lgkmcnt(0)
	v_mfma_f32_32x32x16_bf16 v[64:79], v[188:191], v[128:131], v[64:79]
	ds_read_b128 v[184:187], v245
	ds_read_b128 v[188:191], v245 offset:8192
	s_waitcnt lgkmcnt(1)
	v_mfma_f32_32x32x16_bf16 v[96:111], v[184:187], v[124:127], v[96:111]
	s_waitcnt lgkmcnt(0)
	v_mfma_f32_32x32x16_bf16 v[64:79], v[188:191], v[124:127], v[64:79]
	ds_read_b128 v[184:187], v246
	ds_read_b128 v[188:191], v246 offset:8192
	s_waitcnt lgkmcnt(1)
	v_mfma_f32_32x32x16_bf16 v[96:111], v[184:187], v[120:123], v[96:111]
	s_waitcnt lgkmcnt(0)
	v_mfma_f32_32x32x16_bf16 v[64:79], v[188:191], v[120:123], v[64:79]
	ds_read_b128 v[184:187], v247
	ds_read_b128 v[188:191], v247 offset:8192
	s_waitcnt lgkmcnt(1)
	v_mfma_f32_32x32x16_bf16 v[96:111], v[184:187], v[116:119], v[96:111]
	s_waitcnt lgkmcnt(0)
	v_mfma_f32_32x32x16_bf16 v[64:79], v[188:191], v[116:119], v[64:79]
	ds_read_b128 v[184:187], v248
	ds_read_b128 v[188:191], v248 offset:8192
	v_cvt_pk_bf16_f32 v92, v192, v193
	v_cvt_pk_bf16_f32 v93, v194, v195
	v_cvt_pk_bf16_f32 v94, v216, v217
	v_cvt_pk_bf16_f32 v95, v219, v220
	s_waitcnt lgkmcnt(1)
	v_mfma_f32_32x32x16_bf16 v[96:111], v[184:187], v[112:115], v[96:111]
	v_exp_f32_e32 v185, v84
	v_fma_f32 v84, v165, v169, v192
	v_add_f32_e32 v84, v193, v84
	v_add_f32_e32 v84, v194, v84
	v_add_f32_e32 v84, v195, v84
	v_add_f32_e32 v84, v216, v84
	v_add_f32_e32 v84, v217, v84
	v_add_f32_e32 v84, v219, v84
	v_add_f32_e32 v84, v220, v84
	v_add_f32_e32 v84, v221, v84
	v_add_f32_e32 v84, v222, v84
	v_add_f32_e32 v84, v223, v84
	v_add_f32_e32 v84, v224, v84
	v_add_f32_e32 v84, v225, v84
	v_add_f32_e32 v84, v226, v84
	v_add_f32_e32 v84, v227, v84
	v_add_f32_e32 v84, v228, v84
	v_add_f32_e32 v84, v80, v84
	v_exp_f32_e32 v186, v85
	v_add_f32_e32 v84, v81, v84
	v_exp_f32_e32 v187, v86
	v_add_f32_e32 v84, v82, v84
	v_add_f32_e32 v84, v83, v84
	s_waitcnt lgkmcnt(0)
	v_mfma_f32_32x32x16_bf16 v[64:79], v[188:191], v[112:115], v[64:79]
	v_exp_f32_e32 v188, v88
	v_add_f32_e32 v84, v185, v84
	v_exp_f32_e32 v189, v89
	v_add_f32_e32 v84, v186, v84
	v_exp_f32_e32 v190, v90
	v_add_f32_e32 v84, v187, v84
	v_exp_f32_e32 v191, v91
	v_add_f32_e32 v84, v87, v84
	v_add_f32_e32 v84, v188, v84
	v_add_f32_e32 v84, v189, v84
	v_add_f32_e32 v84, v190, v84
	v_add_f32_e32 v84, v191, v84
	v_add_f32_e32 v84, v229, v84
	v_add_f32_e32 v84, v230, v84
	v_add_f32_e32 v84, v231, v84
	v_add_f32_e32 v152, v232, v84
	v_cvt_pk_bf16_f32 v88, v221, v222
	v_cvt_pk_bf16_f32 v89, v223, v224
	v_cvt_pk_bf16_f32 v90, v225, v226
	v_cvt_pk_bf16_f32 v91, v227, v228
	v_cvt_pk_bf16_f32 v84, v80, v81
	v_cvt_pk_bf16_f32 v85, v82, v83
	v_cvt_pk_bf16_f32 v86, v185, v186
	v_cvt_pk_bf16_f32 v87, v187, v87
	v_cvt_pk_bf16_f32 v80, v188, v189
	v_cvt_pk_bf16_f32 v81, v190, v191
	v_cvt_pk_bf16_f32 v82, v229, v230
	v_cvt_pk_bf16_f32 v83, v231, v232
	s_add_i32 s44, s48, 0
	s_add_i32 s44, s44, 0x10000
	s_waitcnt vmcnt(2)
	ds_write_b128 v204, v[136:139] offset:32768
	s_waitcnt vmcnt(1)
	ds_write_b128 v249, v[140:143] offset:32768
	s_waitcnt vmcnt(0)
	ds_write_b64 v250, v[172:173] offset:32768

; __device__ __forceinline__ s16x4 vtr(lds_cptr p) { return __builtin_bit_cast(s16x4, __builtin_amdgcn_ds_read_tr16_b64_v4i16((LAS v4i16_t*)p)); }
; template <bool FIRST> __device__ __forceinline__ void partialSM(f32x16& p0, f32x16& p1, float& mref, f32x16& negm, float& alpha) {
;   constexpr float THRL = THR * 1.4426950408889634f;
;   float pmax = p0[0];
; #pragma unroll
;   for (int r = 1; r < 16; ++r) pmax = fmaxf(pmax, p0[r]);
; #pragma unroll
;   for (int r = 0; r < 16; ++r) pmax = fmaxf(pmax, p1[r]);
;   { auto rr = __builtin_amdgcn_permlane32_swap(__float_as_uint(pmax), __float_as_uint(pmax), false, false);
;     pmax = fmaxf(__uint_as_float(rr[0]), __uint_as_float(rr[1])); }
;   if (!FIRST && __builtin_expect(__all(pmax <= THRL), 1)) { alpha = 1.f; }
; template <int D0> __device__ __forceinline__ void pv_one(f32x16& od, lds_cptr vp, bf16x8 pa0, bf16x8 pa1, bf16x8 pa2, bf16x8 pa3) {
;   const s16x4 l0 = vtr(vp + v_rd_off(D0, 0, 0)), h0 = vtr(vp + v_rd_off(D0, 0, 1)), l1 = vtr(vp + v_rd_off(D0, 1, 0)), h1 = vtr(vp + v_rd_off(D0, 1, 1));
;   const s16x4 l2 = vtr(vp + v_rd_off(D0, 2, 0)), h2 = vtr(vp + v_rd_off(D0, 2, 1)), l3 = vtr(vp + v_rd_off(D0, 3, 0)), h3 = vtr(vp + v_rd_off(D0, 3, 1));
;     ...
;   od = __builtin_amdgcn_mfma_f32_32x32x16_bf16(pa0, PK(l0, h0), od, 0, 0, 0);
;   od = __builtin_amdgcn_mfma_f32_32x32x16_bf16(pa1, PK(l1, h1), od, 0, 0, 0);
;   od = __builtin_amdgcn_mfma_f32_32x32x16_bf16(pa2, PK(l2, h2), od, 0, 0, 0);
;   od = __builtin_amdgcn_mfma_f32_32x32x16_bf16(pa3, PK(l3, h3), od, 0, 0, 0);
;     ...
; }
; __device__ __forceinline__ void pv_d0(f32x16* o, lds_cptr vp, bf16x8 pa0, bf16x8 pa1, bf16x8 pa2, bf16x8 pa3) {
;   pv_one<0>(o[0], vp, pa0, pa1, pa2, pa3); pv_one<1>(o[1], vp, pa0, pa1, pa2, pa3);
.Lf2_750:
	ds_read_b64_tr_b16 v[180:181], v203 offset:49152
	ds_read_b64_tr_b16 v[182:183], v203 offset:51200
	ds_read_b64_tr_b16 v[188:189], v203 offset:51712
	ds_read_b64_tr_b16 v[186:187], v203 offset:49664
	s_waitcnt lgkmcnt(2)
	v_mfma_f32_32x32x16_bf16 v[0:15], v[92:95], v[180:183], v[0:15]
	ds_read_b64_tr_b16 v[180:181], v203 offset:53248
	ds_read_b64_tr_b16 v[182:183], v203 offset:55296
	ds_read_b64_tr_b16 v[192:193], v203 offset:55808
	ds_read_b64_tr_b16 v[190:191], v203 offset:53760
	s_waitcnt lgkmcnt(2)
	v_mfma_f32_32x32x16_bf16 v[0:15], v[88:91], v[180:183], v[0:15]
	ds_read_b64_tr_b16 v[180:181], v203 offset:57344
	ds_read_b64_tr_b16 v[182:183], v203 offset:59392
	ds_read_b64_tr_b16 v[222:223], v203 offset:59904
	ds_read_b64_tr_b16 v[220:221], v203 offset:57856
	v_mfma_f32_32x32x16_bf16 v[16:31], v[92:95], v[186:189], v[16:31]
	s_waitcnt lgkmcnt(2)
	v_mfma_f32_32x32x16_bf16 v[0:15], v[84:87], v[180:183], v[0:15]
	ds_read_b64_tr_b16 v[180:181], v203 offset:61440
	ds_read_b64_tr_b16 v[182:183], v203 offset:63488
	ds_read_b64_tr_b16 v[226:227], v203 offset:64000
	ds_read_b64_tr_b16 v[224:225], v203 offset:61952
	v_mfma_f32_32x32x16_bf16 v[16:31], v[88:91], v[190:193], v[16:31]
	s_waitcnt lgkmcnt(2)
	v_mfma_f32_32x32x16_bf16 v[0:15], v[80:83], v[180:183], v[0:15]
	v_max_f32_e32 v180, v96, v97
	v_max3_f32 v180, v180, v98, v99
	v_max3_f32 v180, v180, v100, v101
	v_max3_f32 v92, v180, v102, v103
	v_max3_f32 v92, v92, v104, v105
	v_max3_f32 v92, v92, v106, v107
	v_max3_f32 v92, v92, v108, v109
	v_mfma_f32_32x32x16_bf16 v[16:31], v[84:87], v[220:223], v[16:31]
	v_max3_f32 v92, v92, v110, v111
	v_max3_f32 v92, v92, v64, v65
	v_max3_f32 v92, v92, v66, v67
	v_max3_f32 v88, v92, v68, v69
	v_max3_f32 v88, v88, v70, v71
	v_max3_f32 v88, v88, v72, v73
	v_max3_f32 v88, v88, v74, v75
	v_max3_f32 v88, v88, v76, v77
	s_waitcnt lgkmcnt(0)
	v_mfma_f32_32x32x16_bf16 v[16:31], v[80:83], v[224:227], v[16:31]
	v_max3_f32 v88, v88, v78, v79
	v_mov_b32_e32 v89, v88
	s_nop 1
	v_permlane32_swap_b32_e32 v88, v89
	v_max_f32_e32 v85, v88, v89
	v_cmp_ge_f32_e32 vcc, s86, v85
	s_cmp_eq_u64 vcc, exec
	v_mov_b32_e32 v84, 1.0
	s_cbranch_scc0 .Lf2_758

; __device__ __forceinline__ s16x4 vtr(lds_cptr p) { return __builtin_bit_cast(s16x4, __builtin_amdgcn_ds_read_tr16_b64_v4i16((LAS v4i16_t*)p)); }
; template <bool FIRST> __device__ __forceinline__ void partialSM(f32x16& p0, f32x16& p1, float& mref, f32x16& negm, float& alpha) {
;   constexpr float THRL = THR * 1.4426950408889634f;
;   float pmax = p0[0];
; #pragma unroll
;   for (int r = 1; r < 16; ++r) pmax = fmaxf(pmax, p0[r]);
; #pragma unroll
;   for (int r = 0; r < 16; ++r) pmax = fmaxf(pmax, p1[r]);
;   { auto rr = __builtin_amdgcn_permlane32_swap(__float_as_uint(pmax), __float_as_uint(pmax), false, false);
;     pmax = fmaxf(__uint_as_float(rr[0]), __uint_as_float(rr[1])); }
;   if (!FIRST && __builtin_expect(__all(pmax <= THRL), 1)) { alpha = 1.f; }
; template <int D0> __device__ __forceinline__ void pv_one(f32x16& od, lds_cptr vp, bf16x8 pa0, bf16x8 pa1, bf16x8 pa2, bf16x8 pa3) {
;   const s16x4 l0 = vtr(vp + v_rd_off(D0, 0, 0)), h0 = vtr(vp + v_rd_off(D0, 0, 1)), l1 = vtr(vp + v_rd_off(D0, 1, 0)), h1 = vtr(vp + v_rd_off(D0, 1, 1));
;   const s16x4 l2 = vtr(vp + v_rd_off(D0, 2, 0)), h2 = vtr(vp + v_rd_off(D0, 2, 1)), l3 = vtr(vp + v_rd_off(D0, 3, 0)), h3 = vtr(vp + v_rd_off(D0, 3, 1));
;     ...
;   od = __builtin_amdgcn_mfma_f32_32x32x16_bf16(pa0, PK(l0, h0), od, 0, 0, 0);
;   od = __builtin_amdgcn_mfma_f32_32x32x16_bf16(pa1, PK(l1, h1), od, 0, 0, 0);
;   od = __builtin_amdgcn_mfma_f32_32x32x16_bf16(pa2, PK(l2, h2), od, 0, 0, 0);
;   od = __builtin_amdgcn_mfma_f32_32x32x16_bf16(pa3, PK(l3, h3), od, 0, 0, 0);
;     ...
; }
; __device__ __forceinline__ void pv_d0(f32x16* o, lds_cptr vp, bf16x8 pa0, bf16x8 pa1, bf16x8 pa2, bf16x8 pa3) {
;   pv_one<0>(o[0], vp, pa0, pa1, pa2, pa3); pv_one<1>(o[1], vp, pa0, pa1, pa2, pa3);
.LBB0_741:
	s_and_b32 s48, s89, 0xc000
	v_add_u32_e32 v169, s48, v203
	ds_read_b64_tr_b16 v[64:65], v169
	ds_read_b64_tr_b16 v[66:67], v169 offset:2048
	ds_read_b64_tr_b16 v[70:71], v169 offset:2560
	ds_read_b64_tr_b16 v[68:69], v169 offset:512
	s_waitcnt lgkmcnt(2)
	v_mfma_f32_32x32x16_bf16 v[0:15], v[60:63], v[64:67], v[0:15]
	ds_read_b64_tr_b16 v[64:65], v169 offset:4096
	ds_read_b64_tr_b16 v[66:67], v169 offset:6144
	ds_read_b64_tr_b16 v[74:75], v169 offset:6656
	ds_read_b64_tr_b16 v[72:73], v169 offset:4608
	s_waitcnt lgkmcnt(2)
	v_mfma_f32_32x32x16_bf16 v[0:15], v[56:59], v[64:67], v[0:15]
	ds_read_b64_tr_b16 v[64:65], v169 offset:8192
	ds_read_b64_tr_b16 v[66:67], v169 offset:10240
	ds_read_b64_tr_b16 v[78:79], v169 offset:10752
	ds_read_b64_tr_b16 v[76:77], v169 offset:8704
	v_mfma_f32_32x32x16_bf16 v[16:31], v[60:63], v[68:71], v[16:31]
	s_waitcnt lgkmcnt(2)
	v_mfma_f32_32x32x16_bf16 v[0:15], v[52:55], v[64:67], v[0:15]
	ds_read_b64_tr_b16 v[64:65], v169 offset:12288
	ds_read_b64_tr_b16 v[66:67], v169 offset:14336
	ds_read_b64_tr_b16 v[186:187], v169 offset:14848
	ds_read_b64_tr_b16 v[184:185], v169 offset:12800
	v_mfma_f32_32x32x16_bf16 v[16:31], v[56:59], v[72:75], v[16:31]
	s_waitcnt lgkmcnt(2)
	v_mfma_f32_32x32x16_bf16 v[0:15], v[48:51], v[64:67], v[0:15]
	v_max_f32_e32 v64, v96, v97
	v_max3_f32 v64, v64, v98, v99
	v_max3_f32 v60, v64, v100, v101
	v_max3_f32 v60, v60, v102, v103
	v_max3_f32 v60, v60, v104, v105
	v_max3_f32 v60, v60, v106, v107
	v_max3_f32 v60, v60, v108, v109
	v_mfma_f32_32x32x16_bf16 v[16:31], v[52:55], v[76:79], v[16:31]
	v_max3_f32 v60, v60, v110, v111
	v_max3_f32 v60, v60, v80, v81
	v_max3_f32 v56, v60, v82, v83
	v_max3_f32 v56, v56, v84, v85
	v_max3_f32 v56, v56, v86, v87
	v_max3_f32 v56, v56, v88, v89
	v_max3_f32 v56, v56, v90, v91
	v_max3_f32 v56, v56, v92, v93
	s_waitcnt lgkmcnt(0)
	v_mfma_f32_32x32x16_bf16 v[16:31], v[48:51], v[184:187], v[16:31]
	v_max3_f32 v56, v56, v94, v95
	v_mov_b32_e32 v52, v56
	s_nop 1
	v_permlane32_swap_b32_e32 v56, v52
	v_max_f32_e32 v52, v56, v52
	v_cmp_ge_f32_e32 vcc, s86, v52
	s_cmp_eq_u64 vcc, exec
	s_cbranch_scc0 .LBB0_757
	v_mov_b32_e32 v169, 1.0

; __device__ __forceinline__ s16x4 vtr(lds_cptr p) { return __builtin_bit_cast(s16x4, __builtin_amdgcn_ds_read_tr16_b64_v4i16((LAS v4i16_t*)p)); }
; template <bool FIRST> __device__ __forceinline__ void partialSM(f32x16& p0, f32x16& p1, float& mref, f32x16& negm, float& alpha) {
;   constexpr float THRL = THR * 1.4426950408889634f;
;   float pmax = p0[0];
; #pragma unroll
;   for (int r = 1; r < 16; ++r) pmax = fmaxf(pmax, p0[r]);
; #pragma unroll
;   for (int r = 0; r < 16; ++r) pmax = fmaxf(pmax, p1[r]);
;   { auto rr = __builtin_amdgcn_permlane32_swap(__float_as_uint(pmax), __float_as_uint(pmax), false, false);
;     pmax = fmaxf(__uint_as_float(rr[0]), __uint_as_float(rr[1])); }
;   if (!FIRST && __builtin_expect(__all(pmax <= THRL), 1)) { alpha = 1.f; }
; template <int D0> __device__ __forceinline__ void pv_one(f32x16& od, lds_cptr vp, bf16x8 pa0, bf16x8 pa1, bf16x8 pa2, bf16x8 pa3) {
;   const s16x4 l0 = vtr(vp + v_rd_off(D0, 0, 0)), h0 = vtr(vp + v_rd_off(D0, 0, 1)), l1 = vtr(vp + v_rd_off(D0, 1, 0)), h1 = vtr(vp + v_rd_off(D0, 1, 1));
;   const s16x4 l2 = vtr(vp + v_rd_off(D0, 2, 0)), h2 = vtr(vp + v_rd_off(D0, 2, 1)), l3 = vtr(vp + v_rd_off(D0, 3, 0)), h3 = vtr(vp + v_rd_off(D0, 3, 1));
;     ...
;   od = __builtin_amdgcn_mfma_f32_32x32x16_bf16(pa0, PK(l0, h0), od, 0, 0, 0);
;   od = __builtin_amdgcn_mfma_f32_32x32x16_bf16(pa1, PK(l1, h1), od, 0, 0, 0);
;   od = __builtin_amdgcn_mfma_f32_32x32x16_bf16(pa2, PK(l2, h2), od, 0, 0, 0);
;   od = __builtin_amdgcn_mfma_f32_32x32x16_bf16(pa3, PK(l3, h3), od, 0, 0, 0);
;     ...
; }
; __device__ __forceinline__ void pv_d0(f32x16* o, lds_cptr vp, bf16x8 pa0, bf16x8 pa1, bf16x8 pa2, bf16x8 pa3) {
;   pv_one<0>(o[0], vp, pa0, pa1, pa2, pa3); pv_one<1>(o[1], vp, pa0, pa1, pa2, pa3);
.LBB0_750:
	v_add_u32_e32 v185, s41, v203
	ds_read_b64_tr_b16 v[180:181], v185
	ds_read_b64_tr_b16 v[182:183], v185 offset:2048
	ds_read_b64_tr_b16 v[188:189], v185 offset:2560
	ds_read_b64_tr_b16 v[186:187], v185 offset:512
	s_waitcnt lgkmcnt(2)
	v_mfma_f32_32x32x16_bf16 v[0:15], v[92:95], v[180:183], v[0:15]
	ds_read_b64_tr_b16 v[180:181], v185 offset:4096
	ds_read_b64_tr_b16 v[182:183], v185 offset:6144
	ds_read_b64_tr_b16 v[192:193], v185 offset:6656
	ds_read_b64_tr_b16 v[190:191], v185 offset:4608
	s_waitcnt lgkmcnt(2)
	v_mfma_f32_32x32x16_bf16 v[0:15], v[88:91], v[180:183], v[0:15]
	ds_read_b64_tr_b16 v[180:181], v185 offset:8192
	ds_read_b64_tr_b16 v[182:183], v185 offset:10240
	ds_read_b64_tr_b16 v[222:223], v185 offset:10752
	ds_read_b64_tr_b16 v[220:221], v185 offset:8704
	v_mfma_f32_32x32x16_bf16 v[16:31], v[92:95], v[186:189], v[16:31]
	s_waitcnt lgkmcnt(2)
	v_mfma_f32_32x32x16_bf16 v[0:15], v[84:87], v[180:183], v[0:15]
	ds_read_b64_tr_b16 v[180:181], v185 offset:12288
	ds_read_b64_tr_b16 v[182:183], v185 offset:14336
	ds_read_b64_tr_b16 v[226:227], v185 offset:14848
	ds_read_b64_tr_b16 v[224:225], v185 offset:12800
	v_mfma_f32_32x32x16_bf16 v[16:31], v[88:91], v[190:193], v[16:31]
	s_waitcnt lgkmcnt(2)
	v_mfma_f32_32x32x16_bf16 v[0:15], v[80:83], v[180:183], v[0:15]
	v_max_f32_e32 v180, v96, v97
	v_max3_f32 v180, v180, v98, v99
	v_max3_f32 v180, v180, v100, v101
	v_max3_f32 v92, v180, v102, v103
	v_max3_f32 v92, v92, v104, v105
	v_max3_f32 v92, v92, v106, v107
	v_max3_f32 v92, v92, v108, v109
	v_mfma_f32_32x32x16_bf16 v[16:31], v[84:87], v[220:223], v[16:31]
	v_max3_f32 v92, v92, v110, v111
	v_max3_f32 v92, v92, v64, v65
	v_max3_f32 v92, v92, v66, v67
	v_max3_f32 v88, v92, v68, v69
	v_max3_f32 v88, v88, v70, v71
	v_max3_f32 v88, v88, v72, v73
	v_max3_f32 v88, v88, v74, v75
	v_max3_f32 v88, v88, v76, v77
	s_waitcnt lgkmcnt(0)
	v_mfma_f32_32x32x16_bf16 v[16:31], v[80:83], v[224:227], v[16:31]
	v_max3_f32 v88, v88, v78, v79
	v_mov_b32_e32 v89, v88
	s_nop 1
	v_permlane32_swap_b32_e32 v88, v89
	v_max_f32_e32 v85, v88, v89
	v_cmp_ge_f32_e32 vcc, s86, v85
	s_cmp_eq_u64 vcc, exec
	v_mov_b32_e32 v84, 1.0
	s_cbranch_scc0 .LBB0_758

.LBB0_743:
	s_and_saveexec_b64 s[46:47], s[4:5]
	ds_write_b32 v212, v169 offset:128
	s_or_b64 exec, exec, s[46:47]
	s_waitcnt lgkmcnt(0)
	v_add_u32_e32 v76, v200, v205
	ds_read_b128 v[64:67], v76 offset:224
	ds_read_b128 v[68:71], v76 offset:192
	ds_read_b128 v[72:75], v76 offset:160
	ds_read_b128 v[76:79], v76 offset:128
	s_waitcnt lgkmcnt(3)
	v_pk_mul_f32 v[12:13], v[12:13], v[64:65]
	s_waitcnt lgkmcnt(2)
	v_pk_mul_f32 v[8:9], v[8:9], v[68:69]
	s_waitcnt lgkmcnt(1)
	v_pk_mul_f32 v[4:5], v[4:5], v[72:73]
	v_pk_mul_f32 v[14:15], v[14:15], v[66:67]
	v_pk_mul_f32 v[10:11], v[10:11], v[70:71]
	v_pk_mul_f32 v[6:7], v[6:7], v[74:75]
	s_waitcnt lgkmcnt(0)
	v_pk_mul_f32 v[2:3], v[2:3], v[78:79]
	v_pk_mul_f32 v[0:1], v[0:1], v[76:77]
	v_pk_mul_f32 v[28:29], v[28:29], v[64:65]
	v_pk_mul_f32 v[24:25], v[24:25], v[68:69]
	v_pk_mul_f32 v[20:21], v[20:21], v[72:73]
	v_pk_mul_f32 v[30:31], v[30:31], v[66:67]
	v_pk_mul_f32 v[26:27], v[26:27], v[70:71]
	v_pk_mul_f32 v[22:23], v[22:23], v[74:75]
	v_pk_mul_f32 v[18:19], v[18:19], v[78:79]
	v_pk_mul_f32 v[16:17], v[16:17], v[76:77]
	s_branch .LBB0_746
.LBB0_752:
	s_and_saveexec_b64 s[44:45], s[4:5]
	ds_write_b32 v212, v84 offset:128
	s_or_b64 exec, exec, s[44:45]
	s_waitcnt lgkmcnt(0)
	v_add_u32_e32 v85, v200, v205
	ds_read_b128 v[80:83], v85 offset:224
	ds_read_b128 v[86:89], v85 offset:192
	ds_read_b128 v[90:93], v85 offset:160
	ds_read_b128 v[180:183], v85 offset:128
	s_waitcnt lgkmcnt(3)
	v_pk_mul_f32 v[12:13], v[12:13], v[80:81]
	s_waitcnt lgkmcnt(2)
	v_pk_mul_f32 v[8:9], v[8:9], v[86:87]
	s_waitcnt lgkmcnt(1)
	v_pk_mul_f32 v[4:5], v[4:5], v[90:91]
	v_pk_mul_f32 v[14:15], v[14:15], v[82:83]
	v_pk_mul_f32 v[10:11], v[10:11], v[88:89]
	v_pk_mul_f32 v[6:7], v[6:7], v[92:93]
	s_waitcnt lgkmcnt(0)
	v_pk_mul_f32 v[2:3], v[2:3], v[182:183]
	v_pk_mul_f32 v[0:1], v[0:1], v[180:181]
	v_pk_mul_f32 v[28:29], v[28:29], v[80:81]
	v_pk_mul_f32 v[24:25], v[24:25], v[86:87]
	v_pk_mul_f32 v[20:21], v[20:21], v[90:91]
	v_pk_mul_f32 v[30:31], v[30:31], v[82:83]
	v_pk_mul_f32 v[26:27], v[26:27], v[88:89]
	v_pk_mul_f32 v[22:23], v[22:23], v[92:93]
	v_pk_mul_f32 v[18:19], v[18:19], v[182:183]
	v_pk_mul_f32 v[16:17], v[16:17], v[180:181]
	s_branch .LBB0_755
